# GEMM main loops: M0 write moved in front of the address instruction so the s_nop between M0 write and LDS-DMA load is not needed (18 s_nop removed)
# baseline (speedup 1.0000x reference)
.LBB0_211:
	s_add_i32 s38, s8, 2
	s_add_u32 s39, s6, 0x80
	s_addc_u32 s9, s7, 0
	s_add_i32 s69, 0, 0x10000
	s_cmp_eq_u32 s57, s8
	s_cselect_b32 s9, s1, s9
	s_cselect_b32 s8, s0, s39
	v_add_u32_e32 v0, s69, v156
	s_cselect_b32 s59, s35, s37
	s_cselect_b32 s58, s34, s36
	s_add_i32 s39, 0, 0x14000
	ds_read_b128 v[144:147], v0
	ds_read_b128 v[148:151], v0 offset:1024
	ds_read_b128 v[160:163], v0 offset:2048
	ds_read_b128 v[164:167], v0 offset:3072
	v_add_u32_e32 v0, s39, v156
	ds_read_b128 v[168:171], v0
	ds_read_b128 v[172:175], v0 offset:1024
	ds_read_b128 v[176:179], v0 offset:2048
	ds_read_b128 v[180:183], v0 offset:3072
	v_lshl_add_u64 v[218:219], s[6:7], 0, v[140:141]
	s_add_i32 m0, s50, 0xc000
	ds_read_b128 v[184:187], v158
	ds_read_b128 v[188:191], v158 offset:1024
	ds_read_b128 v[192:195], v158 offset:2048
	ds_read_b128 v[196:199], v158 offset:3072
	ds_read_b128 v[202:205], v158 offset:4096
	ds_read_b128 v[206:209], v158 offset:5120
	ds_read_b128 v[210:213], v158 offset:6144
	ds_read_b128 v[214:217], v158 offset:7168
	global_load_lds_dwordx4 v[218:219], off
	s_add_i32 m0, s50, 0xe000
	v_lshl_add_u64 v[218:219], s[6:7], 0, v[142:143]
	global_load_lds_dwordx4 v[218:219], off
	s_waitcnt vmcnt(8)
	s_waitcnt lgkmcnt(0)
	s_barrier
	v_mfma_f32_16x16x32_bf16 v[126:129], v[144:147], v[184:187], v[126:129]
	v_mfma_f32_16x16x32_bf16 v[122:125], v[160:163], v[184:187], v[122:125]
	v_mfma_f32_16x16x32_bf16 v[110:113], v[144:147], v[192:195], v[110:113]
	v_mfma_f32_16x16x32_bf16 v[106:109], v[160:163], v[192:195], v[106:109]
	v_mfma_f32_16x16x32_bf16 v[94:97], v[144:147], v[202:205], v[94:97]
	v_mfma_f32_16x16x32_bf16 v[90:93], v[160:163], v[202:205], v[90:93]
	v_mfma_f32_16x16x32_bf16 v[78:81], v[144:147], v[210:213], v[78:81]
	v_mfma_f32_16x16x32_bf16 v[74:77], v[160:163], v[210:213], v[74:77]
	v_mfma_f32_16x16x32_bf16 v[126:129], v[148:151], v[188:191], v[126:129]
	v_mfma_f32_16x16x32_bf16 v[122:125], v[164:167], v[188:191], v[122:125]
	v_mfma_f32_16x16x32_bf16 v[110:113], v[148:151], v[196:199], v[110:113]
	v_mfma_f32_16x16x32_bf16 v[106:109], v[164:167], v[196:199], v[106:109]
	v_mfma_f32_16x16x32_bf16 v[94:97], v[148:151], v[206:209], v[94:97]
	v_mfma_f32_16x16x32_bf16 v[90:93], v[164:167], v[206:209], v[90:93]
	v_mfma_f32_16x16x32_bf16 v[78:81], v[148:151], v[214:217], v[78:81]
	v_mfma_f32_16x16x32_bf16 v[74:77], v[164:167], v[214:217], v[74:77]
	v_mfma_f32_16x16x32_bf16 v[118:121], v[168:171], v[184:187], v[118:121]
	v_mfma_f32_16x16x32_bf16 v[114:117], v[176:179], v[184:187], v[114:117]
	v_mfma_f32_16x16x32_bf16 v[102:105], v[168:171], v[192:195], v[102:105]
	v_mfma_f32_16x16x32_bf16 v[98:101], v[176:179], v[192:195], v[98:101]
	v_mfma_f32_16x16x32_bf16 v[86:89], v[168:171], v[202:205], v[86:89]
	v_mfma_f32_16x16x32_bf16 v[82:85], v[176:179], v[202:205], v[82:85]
	v_mfma_f32_16x16x32_bf16 v[70:73], v[168:171], v[210:213], v[70:73]
	v_mfma_f32_16x16x32_bf16 v[66:69], v[176:179], v[210:213], v[66:69]
	v_mfma_f32_16x16x32_bf16 v[118:121], v[172:175], v[188:191], v[118:121]
	v_mfma_f32_16x16x32_bf16 v[114:117], v[180:183], v[188:191], v[114:117]
	v_mfma_f32_16x16x32_bf16 v[102:105], v[172:175], v[196:199], v[102:105]
	v_mfma_f32_16x16x32_bf16 v[98:101], v[180:183], v[196:199], v[98:101]
	v_mfma_f32_16x16x32_bf16 v[86:89], v[172:175], v[206:209], v[86:89]
	v_mfma_f32_16x16x32_bf16 v[82:85], v[180:183], v[206:209], v[82:85]
	v_mfma_f32_16x16x32_bf16 v[70:73], v[172:175], v[214:217], v[70:73]
	v_mfma_f32_16x16x32_bf16 v[66:69], v[180:183], v[214:217], v[66:69]
	s_barrier
	s_add_i32 s69, s69, s49
	v_lshl_add_u64 v[218:219], s[58:59], 0, v[136:137]
	s_mov_b32 m0, s69
	ds_read_b128 v[184:187], v158 offset:16384
	ds_read_b128 v[188:191], v158 offset:17408
	ds_read_b128 v[192:195], v158 offset:18432
	ds_read_b128 v[196:199], v158 offset:19456
	ds_read_b128 v[202:205], v158 offset:20480
	ds_read_b128 v[206:209], v158 offset:21504
	ds_read_b128 v[210:213], v158 offset:22528
	ds_read_b128 v[214:217], v158 offset:23552
	global_load_lds_dwordx4 v[218:219], off
	s_add_i32 m0, s69, 0x2000
	v_lshl_add_u64 v[220:221], s[58:59], 0, v[132:133]
	s_add_u32 s58, s58, s47
	s_addc_u32 s59, s59, 0
	s_add_i32 s39, s39, s49
	global_load_lds_dwordx4 v[220:221], off
	v_lshl_add_u64 v[222:223], s[58:59], 0, v[136:137]
	s_mov_b32 m0, s39
	v_lshl_add_u64 v[224:225], s[58:59], 0, v[132:133]
	global_load_lds_dwordx4 v[222:223], off
	s_add_i32 m0, s39, 0x2000
	v_lshl_add_u64 v[226:227], s[8:9], 0, v[134:135]
	global_load_lds_dwordx4 v[224:225], off
	s_mov_b32 m0, s50
	v_lshl_add_u64 v[228:229], s[8:9], 0, v[130:131]
	global_load_lds_dwordx4 v[226:227], off
	s_mov_b32 m0, s51
	s_nop 0
	global_load_lds_dwordx4 v[228:229], off
	s_waitcnt vmcnt(8)
	s_waitcnt lgkmcnt(0)
	s_barrier
	v_mfma_f32_16x16x32_bf16 v[62:65], v[144:147], v[184:187], v[62:65]
	v_mfma_f32_16x16x32_bf16 v[58:61], v[160:163], v[184:187], v[58:61]
	v_mfma_f32_16x16x32_bf16 v[46:49], v[144:147], v[192:195], v[46:49]
	v_mfma_f32_16x16x32_bf16 v[42:45], v[160:163], v[192:195], v[42:45]
	v_mfma_f32_16x16x32_bf16 v[30:33], v[144:147], v[202:205], v[30:33]
	v_mfma_f32_16x16x32_bf16 v[26:29], v[160:163], v[202:205], v[26:29]
	v_mfma_f32_16x16x32_bf16 v[14:17], v[144:147], v[210:213], v[14:17]
	v_mfma_f32_16x16x32_bf16 v[10:13], v[160:163], v[210:213], v[10:13]
	v_mfma_f32_16x16x32_bf16 v[62:65], v[148:151], v[188:191], v[62:65]
	v_mfma_f32_16x16x32_bf16 v[58:61], v[164:167], v[188:191], v[58:61]
	v_mfma_f32_16x16x32_bf16 v[46:49], v[148:151], v[196:199], v[46:49]
	v_mfma_f32_16x16x32_bf16 v[42:45], v[164:167], v[196:199], v[42:45]
	v_mfma_f32_16x16x32_bf16 v[30:33], v[148:151], v[206:209], v[30:33]
	v_mfma_f32_16x16x32_bf16 v[26:29], v[164:167], v[206:209], v[26:29]
	v_mfma_f32_16x16x32_bf16 v[14:17], v[148:151], v[214:217], v[14:17]
	v_mfma_f32_16x16x32_bf16 v[10:13], v[164:167], v[214:217], v[10:13]
	v_mfma_f32_16x16x32_bf16 v[54:57], v[168:171], v[184:187], v[54:57]
	v_mfma_f32_16x16x32_bf16 v[50:53], v[176:179], v[184:187], v[50:53]
	v_mfma_f32_16x16x32_bf16 v[38:41], v[168:171], v[192:195], v[38:41]
	v_mfma_f32_16x16x32_bf16 v[34:37], v[176:179], v[192:195], v[34:37]
	v_mfma_f32_16x16x32_bf16 v[22:25], v[168:171], v[202:205], v[22:25]
	v_mfma_f32_16x16x32_bf16 v[18:21], v[176:179], v[202:205], v[18:21]
	v_mfma_f32_16x16x32_bf16 v[6:9], v[168:171], v[210:213], v[6:9]
	v_mfma_f32_16x16x32_bf16 v[2:5], v[176:179], v[210:213], v[2:5]
	v_mfma_f32_16x16x32_bf16 v[54:57], v[172:175], v[188:191], v[54:57]
	v_mfma_f32_16x16x32_bf16 v[50:53], v[180:183], v[188:191], v[50:53]
	v_mfma_f32_16x16x32_bf16 v[38:41], v[172:175], v[196:199], v[38:41]
	v_mfma_f32_16x16x32_bf16 v[34:37], v[180:183], v[196:199], v[34:37]
	v_mfma_f32_16x16x32_bf16 v[22:25], v[172:175], v[206:209], v[22:25]
	v_mfma_f32_16x16x32_bf16 v[18:21], v[180:183], v[206:209], v[18:21]
	v_mfma_f32_16x16x32_bf16 v[6:9], v[172:175], v[214:217], v[6:9]
	v_mfma_f32_16x16x32_bf16 v[2:5], v[180:183], v[214:217], v[2:5]
	s_barrier
	s_add_i32 s39, 0, 0x18000
	v_add_u32_e32 v0, s39, v156
	s_add_i32 s58, 0, 0x1c000
	ds_read_b128 v[144:147], v0
	ds_read_b128 v[148:151], v0 offset:1024
	ds_read_b128 v[160:163], v0 offset:2048
	ds_read_b128 v[164:167], v0 offset:3072
	v_add_u32_e32 v0, s58, v156
	ds_read_b128 v[168:171], v0
	ds_read_b128 v[172:175], v0 offset:1024
	ds_read_b128 v[176:179], v0 offset:2048
	ds_read_b128 v[180:183], v0 offset:3072
	s_add_u32 s8, s8, s14
	s_addc_u32 s9, s9, 0
	s_mov_b32 m0, s52
	v_lshl_add_u64 v[230:231], s[8:9], 0, v[134:135]
	ds_read_b128 v[184:187], v158 offset:32768
	ds_read_b128 v[188:191], v158 offset:33792
	ds_read_b128 v[192:195], v158 offset:34816
	ds_read_b128 v[196:199], v158 offset:35840
	ds_read_b128 v[202:205], v158 offset:36864
	ds_read_b128 v[206:209], v158 offset:37888
	ds_read_b128 v[210:213], v158 offset:38912
	ds_read_b128 v[214:217], v158 offset:39936
	global_load_lds_dwordx4 v[230:231], off
	s_mov_b32 m0, s53
	v_lshl_add_u64 v[230:231], s[8:9], 0, v[130:131]
	global_load_lds_dwordx4 v[230:231], off
	s_waitcnt vmcnt(8)
	s_waitcnt lgkmcnt(0)
	s_barrier
	v_mfma_f32_16x16x32_bf16 v[126:129], v[144:147], v[184:187], v[126:129]
	v_mfma_f32_16x16x32_bf16 v[122:125], v[160:163], v[184:187], v[122:125]
	v_mfma_f32_16x16x32_bf16 v[110:113], v[144:147], v[192:195], v[110:113]
	v_mfma_f32_16x16x32_bf16 v[106:109], v[160:163], v[192:195], v[106:109]
	v_mfma_f32_16x16x32_bf16 v[94:97], v[144:147], v[202:205], v[94:97]
	v_mfma_f32_16x16x32_bf16 v[90:93], v[160:163], v[202:205], v[90:93]
	v_mfma_f32_16x16x32_bf16 v[78:81], v[144:147], v[210:213], v[78:81]
	v_mfma_f32_16x16x32_bf16 v[74:77], v[160:163], v[210:213], v[74:77]
	v_mfma_f32_16x16x32_bf16 v[126:129], v[148:151], v[188:191], v[126:129]
	v_mfma_f32_16x16x32_bf16 v[122:125], v[164:167], v[188:191], v[122:125]
	v_mfma_f32_16x16x32_bf16 v[110:113], v[148:151], v[196:199], v[110:113]
	v_mfma_f32_16x16x32_bf16 v[106:109], v[164:167], v[196:199], v[106:109]
	v_mfma_f32_16x16x32_bf16 v[94:97], v[148:151], v[206:209], v[94:97]
	v_mfma_f32_16x16x32_bf16 v[90:93], v[164:167], v[206:209], v[90:93]
	v_mfma_f32_16x16x32_bf16 v[78:81], v[148:151], v[214:217], v[78:81]
	v_mfma_f32_16x16x32_bf16 v[74:77], v[164:167], v[214:217], v[74:77]
	v_mfma_f32_16x16x32_bf16 v[118:121], v[168:171], v[184:187], v[118:121]
	v_mfma_f32_16x16x32_bf16 v[114:117], v[176:179], v[184:187], v[114:117]
	v_mfma_f32_16x16x32_bf16 v[102:105], v[168:171], v[192:195], v[102:105]
	v_mfma_f32_16x16x32_bf16 v[98:101], v[176:179], v[192:195], v[98:101]
	v_mfma_f32_16x16x32_bf16 v[86:89], v[168:171], v[202:205], v[86:89]
	v_mfma_f32_16x16x32_bf16 v[82:85], v[176:179], v[202:205], v[82:85]
	v_mfma_f32_16x16x32_bf16 v[70:73], v[168:171], v[210:213], v[70:73]
	v_mfma_f32_16x16x32_bf16 v[66:69], v[176:179], v[210:213], v[66:69]
	v_mfma_f32_16x16x32_bf16 v[118:121], v[172:175], v[188:191], v[118:121]
	v_mfma_f32_16x16x32_bf16 v[114:117], v[180:183], v[188:191], v[114:117]
	v_mfma_f32_16x16x32_bf16 v[102:105], v[172:175], v[196:199], v[102:105]
	v_mfma_f32_16x16x32_bf16 v[98:101], v[180:183], v[196:199], v[98:101]
	v_mfma_f32_16x16x32_bf16 v[86:89], v[172:175], v[206:209], v[86:89]
	v_mfma_f32_16x16x32_bf16 v[82:85], v[180:183], v[206:209], v[82:85]
	v_mfma_f32_16x16x32_bf16 v[70:73], v[172:175], v[214:217], v[70:73]
	v_mfma_f32_16x16x32_bf16 v[66:69], v[180:183], v[214:217], v[66:69]
	s_barrier
	s_add_i32 s8, s39, s49
	v_lshl_add_u64 v[218:219], v[218:219], 0, s[16:17]
	s_mov_b32 m0, s8
	ds_read_b128 v[184:187], v158 offset:49152
	ds_read_b128 v[188:191], v158 offset:50176
	ds_read_b128 v[192:195], v158 offset:51200
	ds_read_b128 v[196:199], v158 offset:52224
	ds_read_b128 v[202:205], v158 offset:53248
	ds_read_b128 v[206:209], v158 offset:54272
	ds_read_b128 v[210:213], v158 offset:55296
	ds_read_b128 v[214:217], v158 offset:56320
	global_load_lds_dwordx4 v[218:219], off
	v_lshl_add_u64 v[218:219], v[220:221], 0, s[16:17]
	s_add_i32 m0, s8, 0x2000
	s_add_i32 s8, s58, s49
	global_load_lds_dwordx4 v[218:219], off
	s_mov_b32 m0, s8
	v_lshl_add_u64 v[218:219], v[222:223], 0, s[16:17]
	global_load_lds_dwordx4 v[218:219], off
	s_add_i32 m0, s8, 0x2000
	v_lshl_add_u64 v[218:219], v[224:225], 0, s[16:17]
	global_load_lds_dwordx4 v[218:219], off
	s_mov_b32 m0, s54
	v_lshl_add_u64 v[218:219], v[226:227], 0, s[16:17]
	global_load_lds_dwordx4 v[218:219], off
	s_mov_b32 m0, s55
	v_lshl_add_u64 v[218:219], v[228:229], 0, s[16:17]
	global_load_lds_dwordx4 v[218:219], off
	s_waitcnt vmcnt(8)
	s_waitcnt lgkmcnt(0)
	s_barrier
	v_mfma_f32_16x16x32_bf16 v[62:65], v[144:147], v[184:187], v[62:65]
	v_mfma_f32_16x16x32_bf16 v[58:61], v[160:163], v[184:187], v[58:61]
	v_mfma_f32_16x16x32_bf16 v[46:49], v[144:147], v[192:195], v[46:49]
	v_mfma_f32_16x16x32_bf16 v[42:45], v[160:163], v[192:195], v[42:45]
	v_mfma_f32_16x16x32_bf16 v[30:33], v[144:147], v[202:205], v[30:33]
	v_mfma_f32_16x16x32_bf16 v[26:29], v[160:163], v[202:205], v[26:29]
	v_mfma_f32_16x16x32_bf16 v[14:17], v[144:147], v[210:213], v[14:17]
	v_mfma_f32_16x16x32_bf16 v[10:13], v[160:163], v[210:213], v[10:13]
	v_mfma_f32_16x16x32_bf16 v[62:65], v[148:151], v[188:191], v[62:65]
	v_mfma_f32_16x16x32_bf16 v[58:61], v[164:167], v[188:191], v[58:61]
	v_mfma_f32_16x16x32_bf16 v[46:49], v[148:151], v[196:199], v[46:49]
	v_mfma_f32_16x16x32_bf16 v[42:45], v[164:167], v[196:199], v[42:45]
	v_mfma_f32_16x16x32_bf16 v[30:33], v[148:151], v[206:209], v[30:33]
	v_mfma_f32_16x16x32_bf16 v[26:29], v[164:167], v[206:209], v[26:29]
	v_mfma_f32_16x16x32_bf16 v[14:17], v[148:151], v[214:217], v[14:17]
	v_mfma_f32_16x16x32_bf16 v[10:13], v[164:167], v[214:217], v[10:13]
	v_mfma_f32_16x16x32_bf16 v[54:57], v[168:171], v[184:187], v[54:57]
	v_mfma_f32_16x16x32_bf16 v[50:53], v[176:179], v[184:187], v[50:53]
	v_mfma_f32_16x16x32_bf16 v[38:41], v[168:171], v[192:195], v[38:41]
	v_mfma_f32_16x16x32_bf16 v[34:37], v[176:179], v[192:195], v[34:37]
	v_mfma_f32_16x16x32_bf16 v[22:25], v[168:171], v[202:205], v[22:25]
	v_mfma_f32_16x16x32_bf16 v[18:21], v[176:179], v[202:205], v[18:21]
	v_mfma_f32_16x16x32_bf16 v[6:9], v[168:171], v[210:213], v[6:9]
	v_mfma_f32_16x16x32_bf16 v[2:5], v[176:179], v[210:213], v[2:5]
	v_mfma_f32_16x16x32_bf16 v[54:57], v[172:175], v[188:191], v[54:57]
	v_mfma_f32_16x16x32_bf16 v[50:53], v[180:183], v[188:191], v[50:53]
	v_mfma_f32_16x16x32_bf16 v[38:41], v[172:175], v[196:199], v[38:41]
	v_mfma_f32_16x16x32_bf16 v[34:37], v[180:183], v[196:199], v[34:37]
	v_mfma_f32_16x16x32_bf16 v[22:25], v[172:175], v[206:209], v[22:25]
	v_mfma_f32_16x16x32_bf16 v[18:21], v[180:183], v[206:209], v[18:21]
	v_mfma_f32_16x16x32_bf16 v[6:9], v[172:175], v[214:217], v[6:9]
	v_mfma_f32_16x16x32_bf16 v[2:5], v[180:183], v[214:217], v[2:5]
	s_barrier
	s_add_u32 s6, s6, 0x100
	s_addc_u32 s7, s7, 0
	s_add_u32 s36, s36, 0x100
	s_addc_u32 s37, s37, 0
	s_cmp_ge_u32 s38, s56
	s_mov_b32 s8, s38
	s_cbranch_scc0 .LBB0_211
	s_and_b64 vcc, exec, s[28:29]
	s_cbranch_vccnz .LBB0_215
	s_lshl_b32 s8, s3, 8
	s_cmp_lt_i32 s45, 2
	s_mov_b64 s[6:7], -1
	s_cbranch_scc0 .LBB0_216

.LBB0_977:
	s_add_i32 s36, s10, 2
	s_add_u32 s37, s8, 0x80
	s_addc_u32 s11, s9, 0
	s_add_i32 s66, 0, 0x10000
	s_cmp_eq_u32 s55, s10
	s_cselect_b32 s11, s1, s11
	s_cselect_b32 s10, s0, s37
	v_add_u32_e32 v0, s66, v156
	s_cselect_b32 s59, s31, s35
	s_cselect_b32 s58, s30, s34
	s_add_i32 s37, 0, 0x14000
	ds_read_b128 v[144:147], v0
	ds_read_b128 v[148:151], v0 offset:1024
	ds_read_b128 v[160:163], v0 offset:2048
	ds_read_b128 v[164:167], v0 offset:3072
	v_add_u32_e32 v0, s37, v156
	ds_read_b128 v[168:171], v0
	ds_read_b128 v[172:175], v0 offset:1024
	ds_read_b128 v[176:179], v0 offset:2048
	ds_read_b128 v[180:183], v0 offset:3072
	v_lshl_add_u64 v[218:219], s[8:9], 0, v[140:141]
	s_add_i32 m0, s48, 0xc000
	ds_read_b128 v[184:187], v158
	ds_read_b128 v[188:191], v158 offset:1024
	ds_read_b128 v[192:195], v158 offset:2048
	ds_read_b128 v[196:199], v158 offset:3072
	ds_read_b128 v[202:205], v158 offset:4096
	ds_read_b128 v[206:209], v158 offset:5120
	ds_read_b128 v[210:213], v158 offset:6144
	ds_read_b128 v[214:217], v158 offset:7168
	global_load_lds_dwordx4 v[218:219], off
	s_add_i32 m0, s48, 0xe000
	v_lshl_add_u64 v[218:219], s[8:9], 0, v[142:143]
	global_load_lds_dwordx4 v[218:219], off
	s_waitcnt vmcnt(8)
	s_waitcnt lgkmcnt(0)
	s_barrier
	v_mfma_f32_16x16x32_bf16 v[126:129], v[144:147], v[184:187], v[126:129]
	v_mfma_f32_16x16x32_bf16 v[122:125], v[160:163], v[184:187], v[122:125]
	v_mfma_f32_16x16x32_bf16 v[110:113], v[144:147], v[192:195], v[110:113]
	v_mfma_f32_16x16x32_bf16 v[106:109], v[160:163], v[192:195], v[106:109]
	v_mfma_f32_16x16x32_bf16 v[94:97], v[144:147], v[202:205], v[94:97]
	v_mfma_f32_16x16x32_bf16 v[90:93], v[160:163], v[202:205], v[90:93]
	v_mfma_f32_16x16x32_bf16 v[78:81], v[144:147], v[210:213], v[78:81]
	v_mfma_f32_16x16x32_bf16 v[74:77], v[160:163], v[210:213], v[74:77]
	v_mfma_f32_16x16x32_bf16 v[126:129], v[148:151], v[188:191], v[126:129]
	v_mfma_f32_16x16x32_bf16 v[122:125], v[164:167], v[188:191], v[122:125]
	v_mfma_f32_16x16x32_bf16 v[110:113], v[148:151], v[196:199], v[110:113]
	v_mfma_f32_16x16x32_bf16 v[106:109], v[164:167], v[196:199], v[106:109]
	v_mfma_f32_16x16x32_bf16 v[94:97], v[148:151], v[206:209], v[94:97]
	v_mfma_f32_16x16x32_bf16 v[90:93], v[164:167], v[206:209], v[90:93]
	v_mfma_f32_16x16x32_bf16 v[78:81], v[148:151], v[214:217], v[78:81]
	v_mfma_f32_16x16x32_bf16 v[74:77], v[164:167], v[214:217], v[74:77]
	v_mfma_f32_16x16x32_bf16 v[118:121], v[168:171], v[184:187], v[118:121]
	v_mfma_f32_16x16x32_bf16 v[114:117], v[176:179], v[184:187], v[114:117]
	v_mfma_f32_16x16x32_bf16 v[102:105], v[168:171], v[192:195], v[102:105]
	v_mfma_f32_16x16x32_bf16 v[98:101], v[176:179], v[192:195], v[98:101]
	v_mfma_f32_16x16x32_bf16 v[86:89], v[168:171], v[202:205], v[86:89]
	v_mfma_f32_16x16x32_bf16 v[82:85], v[176:179], v[202:205], v[82:85]
	v_mfma_f32_16x16x32_bf16 v[70:73], v[168:171], v[210:213], v[70:73]
	v_mfma_f32_16x16x32_bf16 v[66:69], v[176:179], v[210:213], v[66:69]
	v_mfma_f32_16x16x32_bf16 v[118:121], v[172:175], v[188:191], v[118:121]
	v_mfma_f32_16x16x32_bf16 v[114:117], v[180:183], v[188:191], v[114:117]
	v_mfma_f32_16x16x32_bf16 v[102:105], v[172:175], v[196:199], v[102:105]
	v_mfma_f32_16x16x32_bf16 v[98:101], v[180:183], v[196:199], v[98:101]
	v_mfma_f32_16x16x32_bf16 v[86:89], v[172:175], v[206:209], v[86:89]
	v_mfma_f32_16x16x32_bf16 v[82:85], v[180:183], v[206:209], v[82:85]
	v_mfma_f32_16x16x32_bf16 v[70:73], v[172:175], v[214:217], v[70:73]
	v_mfma_f32_16x16x32_bf16 v[66:69], v[180:183], v[214:217], v[66:69]
	s_barrier
	s_add_i32 s66, s66, s47
	v_lshl_add_u64 v[218:219], s[58:59], 0, v[136:137]
	s_mov_b32 m0, s66
	ds_read_b128 v[184:187], v158 offset:16384
	ds_read_b128 v[188:191], v158 offset:17408
	ds_read_b128 v[192:195], v158 offset:18432
	ds_read_b128 v[196:199], v158 offset:19456
	ds_read_b128 v[202:205], v158 offset:20480
	ds_read_b128 v[206:209], v158 offset:21504
	ds_read_b128 v[210:213], v158 offset:22528
	ds_read_b128 v[214:217], v158 offset:23552
	global_load_lds_dwordx4 v[218:219], off
	s_add_i32 m0, s66, 0x2000
	v_lshl_add_u64 v[220:221], s[58:59], 0, v[132:133]
	s_add_u32 s58, s58, s45
	s_addc_u32 s59, s59, 0
	s_add_i32 s37, s37, s47
	global_load_lds_dwordx4 v[220:221], off
	v_lshl_add_u64 v[222:223], s[58:59], 0, v[136:137]
	s_mov_b32 m0, s37
	v_lshl_add_u64 v[224:225], s[58:59], 0, v[132:133]
	global_load_lds_dwordx4 v[222:223], off
	s_add_i32 m0, s37, 0x2000
	v_lshl_add_u64 v[226:227], s[10:11], 0, v[134:135]
	global_load_lds_dwordx4 v[224:225], off
	s_mov_b32 m0, s48
	v_lshl_add_u64 v[228:229], s[10:11], 0, v[130:131]
	global_load_lds_dwordx4 v[226:227], off
	s_mov_b32 m0, s49
	s_nop 0
	global_load_lds_dwordx4 v[228:229], off
	s_waitcnt vmcnt(8)
	s_waitcnt lgkmcnt(0)
	s_barrier
	v_mfma_f32_16x16x32_bf16 v[62:65], v[144:147], v[184:187], v[62:65]
	v_mfma_f32_16x16x32_bf16 v[58:61], v[160:163], v[184:187], v[58:61]
	v_mfma_f32_16x16x32_bf16 v[46:49], v[144:147], v[192:195], v[46:49]
	v_mfma_f32_16x16x32_bf16 v[42:45], v[160:163], v[192:195], v[42:45]
	v_mfma_f32_16x16x32_bf16 v[30:33], v[144:147], v[202:205], v[30:33]
	v_mfma_f32_16x16x32_bf16 v[26:29], v[160:163], v[202:205], v[26:29]
	v_mfma_f32_16x16x32_bf16 v[14:17], v[144:147], v[210:213], v[14:17]
	v_mfma_f32_16x16x32_bf16 v[10:13], v[160:163], v[210:213], v[10:13]
	v_mfma_f32_16x16x32_bf16 v[62:65], v[148:151], v[188:191], v[62:65]
	v_mfma_f32_16x16x32_bf16 v[58:61], v[164:167], v[188:191], v[58:61]
	v_mfma_f32_16x16x32_bf16 v[46:49], v[148:151], v[196:199], v[46:49]
	v_mfma_f32_16x16x32_bf16 v[42:45], v[164:167], v[196:199], v[42:45]
	v_mfma_f32_16x16x32_bf16 v[30:33], v[148:151], v[206:209], v[30:33]
	v_mfma_f32_16x16x32_bf16 v[26:29], v[164:167], v[206:209], v[26:29]
	v_mfma_f32_16x16x32_bf16 v[14:17], v[148:151], v[214:217], v[14:17]
	v_mfma_f32_16x16x32_bf16 v[10:13], v[164:167], v[214:217], v[10:13]
	v_mfma_f32_16x16x32_bf16 v[54:57], v[168:171], v[184:187], v[54:57]
	v_mfma_f32_16x16x32_bf16 v[50:53], v[176:179], v[184:187], v[50:53]
	v_mfma_f32_16x16x32_bf16 v[38:41], v[168:171], v[192:195], v[38:41]
	v_mfma_f32_16x16x32_bf16 v[34:37], v[176:179], v[192:195], v[34:37]
	v_mfma_f32_16x16x32_bf16 v[22:25], v[168:171], v[202:205], v[22:25]
	v_mfma_f32_16x16x32_bf16 v[18:21], v[176:179], v[202:205], v[18:21]
	v_mfma_f32_16x16x32_bf16 v[6:9], v[168:171], v[210:213], v[6:9]
	v_mfma_f32_16x16x32_bf16 v[2:5], v[176:179], v[210:213], v[2:5]
	v_mfma_f32_16x16x32_bf16 v[54:57], v[172:175], v[188:191], v[54:57]
	v_mfma_f32_16x16x32_bf16 v[50:53], v[180:183], v[188:191], v[50:53]
	v_mfma_f32_16x16x32_bf16 v[38:41], v[172:175], v[196:199], v[38:41]
	v_mfma_f32_16x16x32_bf16 v[34:37], v[180:183], v[196:199], v[34:37]
	v_mfma_f32_16x16x32_bf16 v[22:25], v[172:175], v[206:209], v[22:25]
	v_mfma_f32_16x16x32_bf16 v[18:21], v[180:183], v[206:209], v[18:21]
	v_mfma_f32_16x16x32_bf16 v[6:9], v[172:175], v[214:217], v[6:9]
	v_mfma_f32_16x16x32_bf16 v[2:5], v[180:183], v[214:217], v[2:5]
	s_barrier
	s_add_i32 s37, 0, 0x18000
	v_add_u32_e32 v0, s37, v156
	s_add_i32 s58, 0, 0x1c000
	ds_read_b128 v[144:147], v0
	ds_read_b128 v[148:151], v0 offset:1024
	ds_read_b128 v[160:163], v0 offset:2048
	ds_read_b128 v[164:167], v0 offset:3072
	v_add_u32_e32 v0, s58, v156
	ds_read_b128 v[168:171], v0
	ds_read_b128 v[172:175], v0 offset:1024
	ds_read_b128 v[176:179], v0 offset:2048
	ds_read_b128 v[180:183], v0 offset:3072
	s_add_u32 s10, s10, s12
	s_addc_u32 s11, s11, 0
	s_mov_b32 m0, s50
	v_lshl_add_u64 v[230:231], s[10:11], 0, v[134:135]
	ds_read_b128 v[184:187], v158 offset:32768
	ds_read_b128 v[188:191], v158 offset:33792
	ds_read_b128 v[192:195], v158 offset:34816
	ds_read_b128 v[196:199], v158 offset:35840
	ds_read_b128 v[202:205], v158 offset:36864
	ds_read_b128 v[206:209], v158 offset:37888
	ds_read_b128 v[210:213], v158 offset:38912
	ds_read_b128 v[214:217], v158 offset:39936
	global_load_lds_dwordx4 v[230:231], off
	s_mov_b32 m0, s51
	v_lshl_add_u64 v[230:231], s[10:11], 0, v[130:131]
	global_load_lds_dwordx4 v[230:231], off
	s_waitcnt vmcnt(8)
	s_waitcnt lgkmcnt(0)
	s_barrier
	v_mfma_f32_16x16x32_bf16 v[126:129], v[144:147], v[184:187], v[126:129]
	v_mfma_f32_16x16x32_bf16 v[122:125], v[160:163], v[184:187], v[122:125]
	v_mfma_f32_16x16x32_bf16 v[110:113], v[144:147], v[192:195], v[110:113]
	v_mfma_f32_16x16x32_bf16 v[106:109], v[160:163], v[192:195], v[106:109]
	v_mfma_f32_16x16x32_bf16 v[94:97], v[144:147], v[202:205], v[94:97]
	v_mfma_f32_16x16x32_bf16 v[90:93], v[160:163], v[202:205], v[90:93]
	v_mfma_f32_16x16x32_bf16 v[78:81], v[144:147], v[210:213], v[78:81]
	v_mfma_f32_16x16x32_bf16 v[74:77], v[160:163], v[210:213], v[74:77]
	v_mfma_f32_16x16x32_bf16 v[126:129], v[148:151], v[188:191], v[126:129]
	v_mfma_f32_16x16x32_bf16 v[122:125], v[164:167], v[188:191], v[122:125]
	v_mfma_f32_16x16x32_bf16 v[110:113], v[148:151], v[196:199], v[110:113]
	v_mfma_f32_16x16x32_bf16 v[106:109], v[164:167], v[196:199], v[106:109]
	v_mfma_f32_16x16x32_bf16 v[94:97], v[148:151], v[206:209], v[94:97]
	v_mfma_f32_16x16x32_bf16 v[90:93], v[164:167], v[206:209], v[90:93]
	v_mfma_f32_16x16x32_bf16 v[78:81], v[148:151], v[214:217], v[78:81]
	v_mfma_f32_16x16x32_bf16 v[74:77], v[164:167], v[214:217], v[74:77]
	v_mfma_f32_16x16x32_bf16 v[118:121], v[168:171], v[184:187], v[118:121]
	v_mfma_f32_16x16x32_bf16 v[114:117], v[176:179], v[184:187], v[114:117]
	v_mfma_f32_16x16x32_bf16 v[102:105], v[168:171], v[192:195], v[102:105]
	v_mfma_f32_16x16x32_bf16 v[98:101], v[176:179], v[192:195], v[98:101]
	v_mfma_f32_16x16x32_bf16 v[86:89], v[168:171], v[202:205], v[86:89]
	v_mfma_f32_16x16x32_bf16 v[82:85], v[176:179], v[202:205], v[82:85]
	v_mfma_f32_16x16x32_bf16 v[70:73], v[168:171], v[210:213], v[70:73]
	v_mfma_f32_16x16x32_bf16 v[66:69], v[176:179], v[210:213], v[66:69]
	v_mfma_f32_16x16x32_bf16 v[118:121], v[172:175], v[188:191], v[118:121]
	v_mfma_f32_16x16x32_bf16 v[114:117], v[180:183], v[188:191], v[114:117]
	v_mfma_f32_16x16x32_bf16 v[102:105], v[172:175], v[196:199], v[102:105]
	v_mfma_f32_16x16x32_bf16 v[98:101], v[180:183], v[196:199], v[98:101]
	v_mfma_f32_16x16x32_bf16 v[86:89], v[172:175], v[206:209], v[86:89]
	v_mfma_f32_16x16x32_bf16 v[82:85], v[180:183], v[206:209], v[82:85]
	v_mfma_f32_16x16x32_bf16 v[70:73], v[172:175], v[214:217], v[70:73]
	v_mfma_f32_16x16x32_bf16 v[66:69], v[180:183], v[214:217], v[66:69]
	s_barrier
	s_add_i32 s10, s37, s47
	v_lshl_add_u64 v[218:219], v[218:219], 0, s[14:15]
	s_mov_b32 m0, s10
	ds_read_b128 v[184:187], v158 offset:49152
	ds_read_b128 v[188:191], v158 offset:50176
	ds_read_b128 v[192:195], v158 offset:51200
	ds_read_b128 v[196:199], v158 offset:52224
	ds_read_b128 v[202:205], v158 offset:53248
	ds_read_b128 v[206:209], v158 offset:54272
	ds_read_b128 v[210:213], v158 offset:55296
	ds_read_b128 v[214:217], v158 offset:56320
	global_load_lds_dwordx4 v[218:219], off
	v_lshl_add_u64 v[218:219], v[220:221], 0, s[14:15]
	s_add_i32 m0, s10, 0x2000
	s_add_i32 s10, s58, s47
	global_load_lds_dwordx4 v[218:219], off
	s_mov_b32 m0, s10
	v_lshl_add_u64 v[218:219], v[222:223], 0, s[14:15]
	global_load_lds_dwordx4 v[218:219], off
	s_add_i32 m0, s10, 0x2000
	v_lshl_add_u64 v[218:219], v[224:225], 0, s[14:15]
	global_load_lds_dwordx4 v[218:219], off
	s_mov_b32 m0, s53
	v_lshl_add_u64 v[218:219], v[226:227], 0, s[14:15]
	global_load_lds_dwordx4 v[218:219], off
	s_mov_b32 m0, s54
	v_lshl_add_u64 v[218:219], v[228:229], 0, s[14:15]
	global_load_lds_dwordx4 v[218:219], off
	s_waitcnt vmcnt(8)
	s_waitcnt lgkmcnt(0)
	s_barrier
	v_mfma_f32_16x16x32_bf16 v[62:65], v[144:147], v[184:187], v[62:65]
	v_mfma_f32_16x16x32_bf16 v[58:61], v[160:163], v[184:187], v[58:61]
	v_mfma_f32_16x16x32_bf16 v[46:49], v[144:147], v[192:195], v[46:49]
	v_mfma_f32_16x16x32_bf16 v[42:45], v[160:163], v[192:195], v[42:45]
	v_mfma_f32_16x16x32_bf16 v[30:33], v[144:147], v[202:205], v[30:33]
	v_mfma_f32_16x16x32_bf16 v[26:29], v[160:163], v[202:205], v[26:29]
	v_mfma_f32_16x16x32_bf16 v[14:17], v[144:147], v[210:213], v[14:17]
	v_mfma_f32_16x16x32_bf16 v[10:13], v[160:163], v[210:213], v[10:13]
	v_mfma_f32_16x16x32_bf16 v[62:65], v[148:151], v[188:191], v[62:65]
	v_mfma_f32_16x16x32_bf16 v[58:61], v[164:167], v[188:191], v[58:61]
	v_mfma_f32_16x16x32_bf16 v[46:49], v[148:151], v[196:199], v[46:49]
	v_mfma_f32_16x16x32_bf16 v[42:45], v[164:167], v[196:199], v[42:45]
	v_mfma_f32_16x16x32_bf16 v[30:33], v[148:151], v[206:209], v[30:33]
	v_mfma_f32_16x16x32_bf16 v[26:29], v[164:167], v[206:209], v[26:29]
	v_mfma_f32_16x16x32_bf16 v[14:17], v[148:151], v[214:217], v[14:17]
	v_mfma_f32_16x16x32_bf16 v[10:13], v[164:167], v[214:217], v[10:13]
	v_mfma_f32_16x16x32_bf16 v[54:57], v[168:171], v[184:187], v[54:57]
	v_mfma_f32_16x16x32_bf16 v[50:53], v[176:179], v[184:187], v[50:53]
	v_mfma_f32_16x16x32_bf16 v[38:41], v[168:171], v[192:195], v[38:41]
	v_mfma_f32_16x16x32_bf16 v[34:37], v[176:179], v[192:195], v[34:37]
	v_mfma_f32_16x16x32_bf16 v[22:25], v[168:171], v[202:205], v[22:25]
	v_mfma_f32_16x16x32_bf16 v[18:21], v[176:179], v[202:205], v[18:21]
	v_mfma_f32_16x16x32_bf16 v[6:9], v[168:171], v[210:213], v[6:9]
	v_mfma_f32_16x16x32_bf16 v[2:5], v[176:179], v[210:213], v[2:5]
	v_mfma_f32_16x16x32_bf16 v[54:57], v[172:175], v[188:191], v[54:57]
	v_mfma_f32_16x16x32_bf16 v[50:53], v[180:183], v[188:191], v[50:53]
	v_mfma_f32_16x16x32_bf16 v[38:41], v[172:175], v[196:199], v[38:41]
	v_mfma_f32_16x16x32_bf16 v[34:37], v[180:183], v[196:199], v[34:37]
	v_mfma_f32_16x16x32_bf16 v[22:25], v[172:175], v[206:209], v[22:25]
	v_mfma_f32_16x16x32_bf16 v[18:21], v[180:183], v[206:209], v[18:21]
	v_mfma_f32_16x16x32_bf16 v[6:9], v[172:175], v[214:217], v[6:9]
	v_mfma_f32_16x16x32_bf16 v[2:5], v[180:183], v[214:217], v[2:5]
	s_barrier
	s_add_u32 s8, s8, 0x100
	s_addc_u32 s9, s9, 0
	s_add_u32 s34, s34, 0x100
	s_addc_u32 s35, s35, 0
	s_cmp_ge_u32 s36, s52
	s_mov_b32 s10, s36
	s_cbranch_scc0 .LBB0_977

.Lg2_first:
	s_mov_b32 s32, 0
	s_add_i32 s36, s10, 2
	s_add_u32 s37, s8, 0x80
	s_addc_u32 s11, s9, 0
	s_add_i32 s66, 0, 0x10000
	s_cmp_eq_u32 s55, s10
	s_cselect_b32 s11, s1, s11
	s_cselect_b32 s10, s0, s37
	v_add_u32_e32 v0, s66, v156
	s_cselect_b32 s59, s31, s35
	s_cselect_b32 s58, s30, s34
	s_add_i32 s37, 0, 0x14000
	ds_read_b128 v[144:147], v0
	ds_read_b128 v[148:151], v0 offset:1024
	ds_read_b128 v[160:163], v0 offset:2048
	ds_read_b128 v[164:167], v0 offset:3072
	v_add_u32_e32 v0, s37, v156
	ds_read_b128 v[168:171], v0
	ds_read_b128 v[172:175], v0 offset:1024
	ds_read_b128 v[176:179], v0 offset:2048
	ds_read_b128 v[180:183], v0 offset:3072
	v_lshl_add_u64 v[218:219], s[8:9], 0, v[140:141]
	s_add_i32 m0, s48, 0xc000
	ds_read_b128 v[184:187], v158
	ds_read_b128 v[188:191], v158 offset:1024
	ds_read_b128 v[192:195], v158 offset:2048
	ds_read_b128 v[196:199], v158 offset:3072
	ds_read_b128 v[202:205], v158 offset:4096
	ds_read_b128 v[206:209], v158 offset:5120
	ds_read_b128 v[210:213], v158 offset:6144
	ds_read_b128 v[214:217], v158 offset:7168
	global_load_lds_dwordx4 v[218:219], off
	s_add_i32 m0, s48, 0xe000
	v_lshl_add_u64 v[218:219], s[8:9], 0, v[142:143]
	global_load_lds_dwordx4 v[218:219], off
	s_waitcnt lgkmcnt(0)
	s_barrier
	v_mfma_f32_16x16x32_bf16 v[126:129], v[144:147], v[184:187], 0
	v_mfma_f32_16x16x32_bf16 v[122:125], v[160:163], v[184:187], 0
	v_mfma_f32_16x16x32_bf16 v[110:113], v[144:147], v[192:195], 0
	v_mfma_f32_16x16x32_bf16 v[106:109], v[160:163], v[192:195], 0
	v_mfma_f32_16x16x32_bf16 v[94:97], v[144:147], v[202:205], 0
	v_mfma_f32_16x16x32_bf16 v[90:93], v[160:163], v[202:205], 0
	v_mfma_f32_16x16x32_bf16 v[78:81], v[144:147], v[210:213], 0
	v_mfma_f32_16x16x32_bf16 v[74:77], v[160:163], v[210:213], 0
	v_mfma_f32_16x16x32_bf16 v[126:129], v[148:151], v[188:191], v[126:129]
	v_mfma_f32_16x16x32_bf16 v[122:125], v[164:167], v[188:191], v[122:125]
	v_mfma_f32_16x16x32_bf16 v[110:113], v[148:151], v[196:199], v[110:113]
	v_mfma_f32_16x16x32_bf16 v[106:109], v[164:167], v[196:199], v[106:109]
	v_mfma_f32_16x16x32_bf16 v[94:97], v[148:151], v[206:209], v[94:97]
	v_mfma_f32_16x16x32_bf16 v[90:93], v[164:167], v[206:209], v[90:93]
	v_mfma_f32_16x16x32_bf16 v[78:81], v[148:151], v[214:217], v[78:81]
	v_mfma_f32_16x16x32_bf16 v[74:77], v[164:167], v[214:217], v[74:77]
	v_mfma_f32_16x16x32_bf16 v[118:121], v[168:171], v[184:187], 0
	v_mfma_f32_16x16x32_bf16 v[114:117], v[176:179], v[184:187], 0
	v_mfma_f32_16x16x32_bf16 v[102:105], v[168:171], v[192:195], 0
	v_mfma_f32_16x16x32_bf16 v[98:101], v[176:179], v[192:195], 0
	v_mfma_f32_16x16x32_bf16 v[86:89], v[168:171], v[202:205], 0
	v_mfma_f32_16x16x32_bf16 v[82:85], v[176:179], v[202:205], 0
	v_mfma_f32_16x16x32_bf16 v[70:73], v[168:171], v[210:213], 0
	v_mfma_f32_16x16x32_bf16 v[66:69], v[176:179], v[210:213], 0
	v_mfma_f32_16x16x32_bf16 v[118:121], v[172:175], v[188:191], v[118:121]
	v_mfma_f32_16x16x32_bf16 v[114:117], v[180:183], v[188:191], v[114:117]
	v_mfma_f32_16x16x32_bf16 v[102:105], v[172:175], v[196:199], v[102:105]
	v_mfma_f32_16x16x32_bf16 v[98:101], v[180:183], v[196:199], v[98:101]
	v_mfma_f32_16x16x32_bf16 v[86:89], v[172:175], v[206:209], v[86:89]
	v_mfma_f32_16x16x32_bf16 v[82:85], v[180:183], v[206:209], v[82:85]
	v_mfma_f32_16x16x32_bf16 v[70:73], v[172:175], v[214:217], v[70:73]
	v_mfma_f32_16x16x32_bf16 v[66:69], v[180:183], v[214:217], v[66:69]
	s_barrier
	s_add_i32 s66, s66, s47
	v_lshl_add_u64 v[218:219], s[58:59], 0, v[136:137]
	s_mov_b32 m0, s66
	ds_read_b128 v[184:187], v158 offset:16384
	ds_read_b128 v[188:191], v158 offset:17408
	ds_read_b128 v[192:195], v158 offset:18432
	ds_read_b128 v[196:199], v158 offset:19456
	ds_read_b128 v[202:205], v158 offset:20480
	ds_read_b128 v[206:209], v158 offset:21504
	ds_read_b128 v[210:213], v158 offset:22528
	ds_read_b128 v[214:217], v158 offset:23552
	global_load_lds_dwordx4 v[218:219], off
	s_add_i32 m0, s66, 0x2000
	v_lshl_add_u64 v[220:221], s[58:59], 0, v[132:133]
	s_add_u32 s58, s58, s45
	s_addc_u32 s59, s59, 0
	s_add_i32 s37, s37, s47
	global_load_lds_dwordx4 v[220:221], off
	v_lshl_add_u64 v[222:223], s[58:59], 0, v[136:137]
	s_mov_b32 m0, s37
	v_lshl_add_u64 v[224:225], s[58:59], 0, v[132:133]
	global_load_lds_dwordx4 v[222:223], off
	s_add_i32 m0, s37, 0x2000
	v_lshl_add_u64 v[226:227], s[10:11], 0, v[134:135]
	global_load_lds_dwordx4 v[224:225], off
	s_mov_b32 m0, s48
	v_lshl_add_u64 v[228:229], s[10:11], 0, v[130:131]
	global_load_lds_dwordx4 v[226:227], off
	s_mov_b32 m0, s49
	s_nop 0
	global_load_lds_dwordx4 v[228:229], off
	s_waitcnt lgkmcnt(0)
	s_barrier
	v_mfma_f32_16x16x32_bf16 v[62:65], v[144:147], v[184:187], 0
	v_mfma_f32_16x16x32_bf16 v[58:61], v[160:163], v[184:187], 0
	v_mfma_f32_16x16x32_bf16 v[46:49], v[144:147], v[192:195], 0
	v_mfma_f32_16x16x32_bf16 v[42:45], v[160:163], v[192:195], 0
	v_mfma_f32_16x16x32_bf16 v[30:33], v[144:147], v[202:205], 0
	v_mfma_f32_16x16x32_bf16 v[26:29], v[160:163], v[202:205], 0
	v_mfma_f32_16x16x32_bf16 v[14:17], v[144:147], v[210:213], 0
	v_mfma_f32_16x16x32_bf16 v[10:13], v[160:163], v[210:213], 0
	v_mfma_f32_16x16x32_bf16 v[62:65], v[148:151], v[188:191], v[62:65]
	v_mfma_f32_16x16x32_bf16 v[58:61], v[164:167], v[188:191], v[58:61]
	v_mfma_f32_16x16x32_bf16 v[46:49], v[148:151], v[196:199], v[46:49]
	v_mfma_f32_16x16x32_bf16 v[42:45], v[164:167], v[196:199], v[42:45]
	v_mfma_f32_16x16x32_bf16 v[30:33], v[148:151], v[206:209], v[30:33]
	v_mfma_f32_16x16x32_bf16 v[26:29], v[164:167], v[206:209], v[26:29]
	v_mfma_f32_16x16x32_bf16 v[14:17], v[148:151], v[214:217], v[14:17]
	v_mfma_f32_16x16x32_bf16 v[10:13], v[164:167], v[214:217], v[10:13]
	v_mfma_f32_16x16x32_bf16 v[54:57], v[168:171], v[184:187], 0
	v_mfma_f32_16x16x32_bf16 v[50:53], v[176:179], v[184:187], 0
	v_mfma_f32_16x16x32_bf16 v[38:41], v[168:171], v[192:195], 0
	v_mfma_f32_16x16x32_bf16 v[34:37], v[176:179], v[192:195], 0
	v_mfma_f32_16x16x32_bf16 v[22:25], v[168:171], v[202:205], 0
	v_mfma_f32_16x16x32_bf16 v[18:21], v[176:179], v[202:205], 0
	v_mfma_f32_16x16x32_bf16 v[6:9], v[168:171], v[210:213], 0
	v_mfma_f32_16x16x32_bf16 v[2:5], v[176:179], v[210:213], 0
	v_mfma_f32_16x16x32_bf16 v[54:57], v[172:175], v[188:191], v[54:57]
	v_mfma_f32_16x16x32_bf16 v[50:53], v[180:183], v[188:191], v[50:53]
	v_mfma_f32_16x16x32_bf16 v[38:41], v[172:175], v[196:199], v[38:41]
	v_mfma_f32_16x16x32_bf16 v[34:37], v[180:183], v[196:199], v[34:37]
	v_mfma_f32_16x16x32_bf16 v[22:25], v[172:175], v[206:209], v[22:25]
	v_mfma_f32_16x16x32_bf16 v[18:21], v[180:183], v[206:209], v[18:21]
	v_mfma_f32_16x16x32_bf16 v[6:9], v[172:175], v[214:217], v[6:9]
	v_mfma_f32_16x16x32_bf16 v[2:5], v[180:183], v[214:217], v[2:5]
	s_barrier
	s_add_i32 s37, 0, 0x18000
	v_add_u32_e32 v0, s37, v156
	s_add_i32 s58, 0, 0x1c000
	ds_read_b128 v[144:147], v0
	ds_read_b128 v[148:151], v0 offset:1024
	ds_read_b128 v[160:163], v0 offset:2048
	ds_read_b128 v[164:167], v0 offset:3072
	v_add_u32_e32 v0, s58, v156
	ds_read_b128 v[168:171], v0
	ds_read_b128 v[172:175], v0 offset:1024
	ds_read_b128 v[176:179], v0 offset:2048
	ds_read_b128 v[180:183], v0 offset:3072
	s_add_u32 s10, s10, s12
	s_addc_u32 s11, s11, 0
	s_mov_b32 m0, s50
	v_lshl_add_u64 v[230:231], s[10:11], 0, v[134:135]
	ds_read_b128 v[184:187], v158 offset:32768
	ds_read_b128 v[188:191], v158 offset:33792
	ds_read_b128 v[192:195], v158 offset:34816
	ds_read_b128 v[196:199], v158 offset:35840
	ds_read_b128 v[202:205], v158 offset:36864
	ds_read_b128 v[206:209], v158 offset:37888
	ds_read_b128 v[210:213], v158 offset:38912
	ds_read_b128 v[214:217], v158 offset:39936
	global_load_lds_dwordx4 v[230:231], off
	s_mov_b32 m0, s51
	v_lshl_add_u64 v[230:231], s[10:11], 0, v[130:131]
	global_load_lds_dwordx4 v[230:231], off
	s_waitcnt vmcnt(8)
	s_waitcnt lgkmcnt(0)
	s_barrier
	v_mfma_f32_16x16x32_bf16 v[126:129], v[144:147], v[184:187], v[126:129]
	v_mfma_f32_16x16x32_bf16 v[122:125], v[160:163], v[184:187], v[122:125]
	v_mfma_f32_16x16x32_bf16 v[110:113], v[144:147], v[192:195], v[110:113]
	v_mfma_f32_16x16x32_bf16 v[106:109], v[160:163], v[192:195], v[106:109]
	v_mfma_f32_16x16x32_bf16 v[94:97], v[144:147], v[202:205], v[94:97]
	v_mfma_f32_16x16x32_bf16 v[90:93], v[160:163], v[202:205], v[90:93]
	v_mfma_f32_16x16x32_bf16 v[78:81], v[144:147], v[210:213], v[78:81]
	v_mfma_f32_16x16x32_bf16 v[74:77], v[160:163], v[210:213], v[74:77]
	v_mfma_f32_16x16x32_bf16 v[126:129], v[148:151], v[188:191], v[126:129]
	v_mfma_f32_16x16x32_bf16 v[122:125], v[164:167], v[188:191], v[122:125]
	v_mfma_f32_16x16x32_bf16 v[110:113], v[148:151], v[196:199], v[110:113]
	v_mfma_f32_16x16x32_bf16 v[106:109], v[164:167], v[196:199], v[106:109]
	v_mfma_f32_16x16x32_bf16 v[94:97], v[148:151], v[206:209], v[94:97]
	v_mfma_f32_16x16x32_bf16 v[90:93], v[164:167], v[206:209], v[90:93]
	v_mfma_f32_16x16x32_bf16 v[78:81], v[148:151], v[214:217], v[78:81]
	v_mfma_f32_16x16x32_bf16 v[74:77], v[164:167], v[214:217], v[74:77]
	v_mfma_f32_16x16x32_bf16 v[118:121], v[168:171], v[184:187], v[118:121]
	v_mfma_f32_16x16x32_bf16 v[114:117], v[176:179], v[184:187], v[114:117]
	v_mfma_f32_16x16x32_bf16 v[102:105], v[168:171], v[192:195], v[102:105]
	v_mfma_f32_16x16x32_bf16 v[98:101], v[176:179], v[192:195], v[98:101]
	v_mfma_f32_16x16x32_bf16 v[86:89], v[168:171], v[202:205], v[86:89]
	v_mfma_f32_16x16x32_bf16 v[82:85], v[176:179], v[202:205], v[82:85]
	v_mfma_f32_16x16x32_bf16 v[70:73], v[168:171], v[210:213], v[70:73]
	v_mfma_f32_16x16x32_bf16 v[66:69], v[176:179], v[210:213], v[66:69]
	v_mfma_f32_16x16x32_bf16 v[118:121], v[172:175], v[188:191], v[118:121]
	v_mfma_f32_16x16x32_bf16 v[114:117], v[180:183], v[188:191], v[114:117]
	v_mfma_f32_16x16x32_bf16 v[102:105], v[172:175], v[196:199], v[102:105]
	v_mfma_f32_16x16x32_bf16 v[98:101], v[180:183], v[196:199], v[98:101]
	v_mfma_f32_16x16x32_bf16 v[86:89], v[172:175], v[206:209], v[86:89]
	v_mfma_f32_16x16x32_bf16 v[82:85], v[180:183], v[206:209], v[82:85]
	v_mfma_f32_16x16x32_bf16 v[70:73], v[172:175], v[214:217], v[70:73]
	v_mfma_f32_16x16x32_bf16 v[66:69], v[180:183], v[214:217], v[66:69]
	s_barrier
	s_add_i32 s10, s37, s47
	v_lshl_add_u64 v[218:219], v[218:219], 0, s[14:15]
	s_mov_b32 m0, s10
	ds_read_b128 v[184:187], v158 offset:49152
	ds_read_b128 v[188:191], v158 offset:50176
	ds_read_b128 v[192:195], v158 offset:51200
	ds_read_b128 v[196:199], v158 offset:52224
	ds_read_b128 v[202:205], v158 offset:53248
	ds_read_b128 v[206:209], v158 offset:54272
	ds_read_b128 v[210:213], v158 offset:55296
	ds_read_b128 v[214:217], v158 offset:56320
	global_load_lds_dwordx4 v[218:219], off
	v_lshl_add_u64 v[218:219], v[220:221], 0, s[14:15]
	s_add_i32 m0, s10, 0x2000
	s_add_i32 s10, s58, s47
	global_load_lds_dwordx4 v[218:219], off
	s_mov_b32 m0, s10
	v_lshl_add_u64 v[218:219], v[222:223], 0, s[14:15]
	global_load_lds_dwordx4 v[218:219], off
	s_add_i32 m0, s10, 0x2000
	v_lshl_add_u64 v[218:219], v[224:225], 0, s[14:15]
	global_load_lds_dwordx4 v[218:219], off
	s_mov_b32 m0, s53
	v_lshl_add_u64 v[218:219], v[226:227], 0, s[14:15]
	global_load_lds_dwordx4 v[218:219], off
	s_mov_b32 m0, s54
	v_lshl_add_u64 v[218:219], v[228:229], 0, s[14:15]
	global_load_lds_dwordx4 v[218:219], off
	s_waitcnt vmcnt(8)
	s_waitcnt lgkmcnt(0)
	s_barrier
	v_mfma_f32_16x16x32_bf16 v[62:65], v[144:147], v[184:187], v[62:65]
	v_mfma_f32_16x16x32_bf16 v[58:61], v[160:163], v[184:187], v[58:61]
	v_mfma_f32_16x16x32_bf16 v[46:49], v[144:147], v[192:195], v[46:49]
	v_mfma_f32_16x16x32_bf16 v[42:45], v[160:163], v[192:195], v[42:45]
	v_mfma_f32_16x16x32_bf16 v[30:33], v[144:147], v[202:205], v[30:33]
	v_mfma_f32_16x16x32_bf16 v[26:29], v[160:163], v[202:205], v[26:29]
	v_mfma_f32_16x16x32_bf16 v[14:17], v[144:147], v[210:213], v[14:17]
	v_mfma_f32_16x16x32_bf16 v[10:13], v[160:163], v[210:213], v[10:13]
	v_mfma_f32_16x16x32_bf16 v[62:65], v[148:151], v[188:191], v[62:65]
	v_mfma_f32_16x16x32_bf16 v[58:61], v[164:167], v[188:191], v[58:61]
	v_mfma_f32_16x16x32_bf16 v[46:49], v[148:151], v[196:199], v[46:49]
	v_mfma_f32_16x16x32_bf16 v[42:45], v[164:167], v[196:199], v[42:45]
	v_mfma_f32_16x16x32_bf16 v[30:33], v[148:151], v[206:209], v[30:33]
	v_mfma_f32_16x16x32_bf16 v[26:29], v[164:167], v[206:209], v[26:29]
	v_mfma_f32_16x16x32_bf16 v[14:17], v[148:151], v[214:217], v[14:17]
	v_mfma_f32_16x16x32_bf16 v[10:13], v[164:167], v[214:217], v[10:13]
	v_mfma_f32_16x16x32_bf16 v[54:57], v[168:171], v[184:187], v[54:57]
	v_mfma_f32_16x16x32_bf16 v[50:53], v[176:179], v[184:187], v[50:53]
	v_mfma_f32_16x16x32_bf16 v[38:41], v[168:171], v[192:195], v[38:41]
	v_mfma_f32_16x16x32_bf16 v[34:37], v[176:179], v[192:195], v[34:37]
	v_mfma_f32_16x16x32_bf16 v[22:25], v[168:171], v[202:205], v[22:25]
	v_mfma_f32_16x16x32_bf16 v[18:21], v[176:179], v[202:205], v[18:21]
	v_mfma_f32_16x16x32_bf16 v[6:9], v[168:171], v[210:213], v[6:9]
	v_mfma_f32_16x16x32_bf16 v[2:5], v[176:179], v[210:213], v[2:5]
	v_mfma_f32_16x16x32_bf16 v[54:57], v[172:175], v[188:191], v[54:57]
	v_mfma_f32_16x16x32_bf16 v[50:53], v[180:183], v[188:191], v[50:53]
	v_mfma_f32_16x16x32_bf16 v[38:41], v[172:175], v[196:199], v[38:41]
	v_mfma_f32_16x16x32_bf16 v[34:37], v[180:183], v[196:199], v[34:37]
	v_mfma_f32_16x16x32_bf16 v[22:25], v[172:175], v[206:209], v[22:25]
	v_mfma_f32_16x16x32_bf16 v[18:21], v[180:183], v[206:209], v[18:21]
	v_mfma_f32_16x16x32_bf16 v[6:9], v[172:175], v[214:217], v[6:9]
	v_mfma_f32_16x16x32_bf16 v[2:5], v[180:183], v[214:217], v[2:5]
	s_barrier
	s_add_u32 s8, s8, 0x100
	s_addc_u32 s9, s9, 0
	s_add_u32 s34, s34, 0x100
	s_addc_u32 s35, s35, 0
	s_cmp_ge_u32 s36, s52
	s_mov_b32 s10, s36
	s_cbranch_scc0 .LBB0_977
	s_branch .Lg2_after
